# GLA output phase: next item's cumulative-gate loads issued ahead of this item's MIX stores so the next item's first wait does not sit behind the stores
# speedup vs baseline: 1.0132x; 1.0132x over previous
; #define LAS __attribute__((address_space(3)))
; __device__ __forceinline__ int crow(int r, int hi) { return (r & 3) + 8 * (r >> 2) + 4 * hi; }
; __device__ __forceinline__ void lds_barrier() { asm volatile("s_waitcnt lgkmcnt(0)\n\ts_barrier" ::: "memory"); }
; __device__ __forceinline__ void gla_c_item(const Args& a, int l, int item, LAS unsigned char* L, int tid, int wave, int lane, bool smp = false) {
;     ...
;         for (int r = 0; r < 16; ++r) OL[(32 * ti + crow(r, hi)) * 132 + 32 * vi + r32] = o[r];
;     }
;     lds_barrier();
;     {
;         const int t = tid >> 3, sg = tid & 7;
;         float x[16]; float q = 0.f;
; #pragma unroll
;         for (int j = 0; j < 4; ++j) { const f32x4 v = *(const LAS f32x4*)(OL + t * 132 + 16 * sg + 4 * j); x[4 * j] = v[0]; x[4 * j + 1] = v[1]; x[4 * j + 2] = v[2]; x[4 * j + 3] = v[3]; q += (v[0] * v[0] + v[1] * v[1]) + (v[2] * v[2] + v[3] * v[3]); }
;         q += __shfl_xor(q, 1); q += __shfl_xor(q, 2); q += __shfl_xor(q, 4);
;         const float rs = rsqrtf(q * (1.0f / 128.0f) + EPS);
;         const float* ng = a.in[11] + l * 128 + 16 * sg;
;         float gt[16];
; #pragma unroll
;         for (int i = 0; i < 4; ++i) { gt[2 * i] = bflo(g0[i]); gt[2 * i + 1] = bfhi(g0[i]); gt[8 + 2 * i] = bflo(g1[i]); gt[8 + 2 * i + 1] = bfhi(g1[i]); }
;         float y[16];
; #pragma unroll
;         for (int i = 0; i < 16; ++i) { const float gv = gt[i]; const float sl = gv / (1.0f + __expf(-gv)); y[i] = x[i] * rs * ng[i] * sl; }
.LBB0_1070:
	s_nop 10
	ds_write2_b32 v90, v2, v3 offset1:132
	v_add_u32_e32 v2, 0x400, v90
	ds_write2_b32 v2, v4, v5 offset0:8 offset1:140
	v_add_u32_e32 v2, 0x1000, v90
	ds_write2_b32 v2, v6, v7 offset0:32 offset1:164
	v_add_u32_e32 v2, 0x1400, v90
	ds_write2_b32 v2, v8, v9 offset0:40 offset1:172
	v_add_u32_e32 v2, 0x2000, v90
	ds_write2_b32 v2, v10, v11 offset0:64 offset1:196
	v_add_u32_e32 v2, 0x2400, v90
	ds_write2_b32 v2, v12, v13 offset0:72 offset1:204
	v_add_u32_e32 v2, 0x3000, v90
	ds_write2_b32 v2, v14, v15 offset0:96 offset1:228
	v_add_u32_e32 v2, 0x3400, v90
	ds_write2_b32 v2, v16, v17 offset0:104 offset1:236
	s_waitcnt lgkmcnt(0)
	s_barrier
	ds_read_b128 v[24:27], v85
	ds_read_b128 v[18:21], v85 offset:16
	ds_read_b128 v[10:13], v85 offset:32
	ds_read_b128 v[2:5], v85 offset:48
	v_readlane_b32 s54, v246, 6
	s_waitcnt lgkmcnt(3)
	v_pk_mul_f32 v[6:7], v[26:27], v[26:27]
	v_pk_mul_f32 v[8:9], v[24:25], v[24:25]
	v_readlane_b32 s55, v246, 7
	v_pk_mov_b32 v[14:15], v[8:9], v[6:7] op_sel:[1,0]
	v_mov_b32_e32 v9, v7
	v_pk_add_f32 v[6:7], v[14:15], v[8:9]
	s_waitcnt lgkmcnt(2)
	v_pk_mul_f32 v[8:9], v[20:21], v[20:21]
	v_pk_mul_f32 v[14:15], v[18:19], v[18:19]
	v_pk_add_f32 v[6:7], v[6:7], v[6:7] op_sel:[0,1] op_sel_hi:[1,0]
	v_pk_mov_b32 v[16:17], v[14:15], v[8:9] op_sel:[1,0]
	v_mov_b32_e32 v15, v9
	v_pk_add_f32 v[8:9], v[16:17], v[14:15]
	s_waitcnt lgkmcnt(0)
	v_mul_f32_e32 v14, v2, v2
	v_mul_f32_e32 v15, v3, v3
	v_pk_add_f32 v[8:9], v[8:9], v[8:9] op_sel:[0,1] op_sel_hi:[1,0]
	v_mov_b32_e32 v7, v14
	v_mov_b32_e32 v9, v15
	v_pk_add_f32 v[6:7], v[6:7], v[8:9]
	v_mul_f32_e32 v8, v11, v11
	v_mul_f32_e32 v14, v13, v13
	v_mul_f32_e32 v16, v4, v4
	v_mul_f32_e32 v17, v5, v5
	v_pk_fma_f32 v[8:9], v[10:11], v[10:11], v[8:9] op_sel_hi:[1,1,0]
	v_pk_fma_f32 v[14:15], v[12:13], v[12:13], v[14:15] op_sel_hi:[1,1,0]
	v_mov_b32_e32 v9, v16
	v_mov_b32_e32 v15, v17
	v_pk_add_f32 v[8:9], v[8:9], v[14:15]
	s_lshl_b32 s82, s82, 1
	v_pk_add_f32 v[6:7], v[6:7], v[8:9]
	v_and_b32_e32 v8, 64, v205
	v_add_f32_e32 v6, v6, v7
	v_xor_b32_e32 v7, 1, v205
	v_add_u32_e32 v8, 64, v8
	v_cmp_lt_i32_e32 vcc, v7, v8
	v_and_b32_e32 v9, 0xffff0000, v38
	v_mov_b32_e32 v65, v1
	v_cndmask_b32_e32 v7, v205, v7, vcc
	v_lshlrev_b32_e32 v7, 2, v7
	ds_bpermute_b32 v7, v7, v6
	v_readlane_b32 s19, v246, 38
	s_add_i32 s18, s18, s52
	s_add_i32 s59, s59, s19
	s_waitcnt lgkmcnt(0)
	v_add_f32_e32 v6, v6, v7
	v_xor_b32_e32 v7, 2, v205
	v_cmp_lt_i32_e32 vcc, v7, v8
	s_nop 1
	v_cndmask_b32_e32 v7, v205, v7, vcc
	v_lshlrev_b32_e32 v7, 2, v7
	ds_bpermute_b32 v7, v7, v6
	s_waitcnt lgkmcnt(0)
	v_add_f32_e32 v6, v6, v7
	v_xor_b32_e32 v7, 4, v205
	v_cmp_lt_i32_e32 vcc, v7, v8
	v_lshlrev_b32_e32 v8, 16, v38
	s_nop 0
	v_cndmask_b32_e32 v7, v205, v7, vcc
	v_lshlrev_b32_e32 v7, 2, v7
	ds_bpermute_b32 v7, v7, v6
	s_waitcnt lgkmcnt(0)
	v_add_f32_e32 v6, v6, v7
	v_fmamk_f32 v6, v6, 0x3c000000, v201
	v_cmp_gt_f32_e32 vcc, s3, v6
	v_mul_f32_e32 v7, 0x4b800000, v6
	s_nop 0
	v_cndmask_b32_e32 v6, v6, v7, vcc
	v_rsq_f32_e32 v6, v6
	s_nop 0
	v_mul_f32_e32 v7, 0x45800000, v6
	v_cndmask_b32_e32 v32, v6, v7, vcc
	v_mul_f32_e32 v6, 0xbfb8aa3b, v8
	v_mul_f32_e32 v7, 0xbfb8aa3b, v9
	v_exp_f32_e32 v6, v6
	v_exp_f32_e32 v7, v7
	v_pk_mul_f32 v[44:45], v[24:25], v[32:33] op_sel_hi:[1,0]
	v_lshlrev_b32_e32 v33, 16, v39
	v_mul_f32_e32 v38, 0xbfb8aa3b, v33
	v_pk_add_f32 v[6:7], v[6:7], 1.0 op_sel_hi:[1,0]
	v_exp_f32_e32 v38, v38
	v_div_scale_f32 v14, vcc, v7, v7, v9
	v_rcp_f32_e32 v15, v14
	v_pk_mul_f32 v[26:27], v[26:27], v[32:33] op_sel_hi:[1,0]
	v_fma_f32 v16, -v14, v15, 1.0
	v_fmac_f32_e32 v15, v16, v15
	v_div_scale_f32 v16, vcc, v9, v7, v9
	v_mul_f32_e32 v17, v16, v15
	v_fma_f32 v22, -v14, v17, v16
	v_fmac_f32_e32 v17, v22, v15
	v_fma_f32 v14, -v14, v17, v16
	v_div_fmas_f32 v14, v14, v15, v17
	v_div_fixup_f32 v43, v14, v7, v9
	v_div_scale_f32 v7, vcc, v6, v6, v8
	v_rcp_f32_e32 v9, v7
	s_nop 0
	v_fma_f32 v14, -v7, v9, 1.0
	v_fmac_f32_e32 v9, v14, v9
	v_div_scale_f32 v14, vcc, v8, v6, v8
	v_mul_f32_e32 v15, v14, v9
	v_fma_f32 v16, -v7, v15, v14
	v_fmac_f32_e32 v15, v16, v9
	v_fma_f32 v7, -v7, v15, v14
	v_div_fmas_f32 v7, v7, v9, v15
	v_div_fixup_f32 v42, v7, v6, v8
	global_load_dwordx4 v[6:9], v[58:59], off offset:48
	global_load_dwordx4 v[14:17], v[58:59], off offset:32
	global_load_dwordx4 v[22:25], v[58:59], off offset:16
	global_load_dwordx4 v[28:31], v[58:59], off
	s_waitcnt vmcnt(0)
; __device__ __forceinline__ void gla_c_item(const Args& a, int l, int item, LAS unsigned char* L, int tid, int wave, int lane, bool smp = false) {
;     ...
;         const float* ng = a.in[11] + l * 128 + 16 * sg;
;         float gt[16];
; #pragma unroll
;         for (int i = 0; i < 4; ++i) { gt[2 * i] = bflo(g0[i]); gt[2 * i + 1] = bfhi(g0[i]); gt[8 + 2 * i] = bflo(g1[i]); gt[8 + 2 * i + 1] = bfhi(g1[i]); }
;         float y[16];
; #pragma unroll
;         for (int i = 0; i < 16; ++i) { const float gv = gt[i]; const float sl = gv / (1.0f + __expf(-gv)); y[i] = x[i] * rs * ng[i] * sl; }
	v_pk_mul_f32 v[28:29], v[28:29], v[44:45]
	s_nop 0
	v_pk_mul_f32 v[28:29], v[42:43], v[28:29]
	v_and_b32_e32 v42, 0xffff0000, v39
	v_mul_f32_e32 v39, 0xbfb8aa3b, v42
	v_exp_f32_e32 v39, v39
	v_pk_mul_f32 v[26:27], v[30:31], v[26:27]
	v_pk_add_f32 v[38:39], v[38:39], 1.0 op_sel_hi:[1,0]
	s_nop 0
	v_div_scale_f32 v43, vcc, v39, v39, v42
	v_rcp_f32_e32 v44, v43
	s_nop 0
	v_fma_f32 v45, -v43, v44, 1.0
	v_fmac_f32_e32 v44, v45, v44
	v_div_scale_f32 v45, vcc, v42, v39, v42
	v_mul_f32_e32 v46, v45, v44
	v_fma_f32 v47, -v43, v46, v45
	v_fmac_f32_e32 v46, v47, v44
	v_fma_f32 v43, -v43, v46, v45
	v_div_fmas_f32 v43, v43, v44, v46
	v_div_fixup_f32 v39, v43, v39, v42
	v_div_scale_f32 v42, vcc, v38, v38, v33
	v_rcp_f32_e32 v43, v42
	s_nop 0
	v_fma_f32 v44, -v42, v43, 1.0
	v_fmac_f32_e32 v43, v44, v43
	v_div_scale_f32 v44, vcc, v33, v38, v33
	v_mul_f32_e32 v45, v44, v43
	v_fma_f32 v46, -v42, v45, v44
	v_fmac_f32_e32 v45, v46, v43
	v_fma_f32 v42, -v42, v45, v44
	v_div_fmas_f32 v42, v42, v43, v45
	v_div_fixup_f32 v38, v42, v38, v33
	v_pk_mul_f32 v[26:27], v[38:39], v[26:27]
	v_lshlrev_b32_e32 v33, 16, v40
	v_and_b32_e32 v38, 0xffff0000, v40
	v_mul_f32_e32 v30, 0xbfb8aa3b, v33
	v_mul_f32_e32 v31, 0xbfb8aa3b, v38
	v_exp_f32_e32 v30, v30
	v_exp_f32_e32 v31, v31
	v_pk_mul_f32 v[18:19], v[18:19], v[32:33] op_sel_hi:[1,0]
	v_pk_add_f32 v[30:31], v[30:31], 1.0 op_sel_hi:[1,0]
	s_nop 0
	v_div_scale_f32 v39, vcc, v31, v31, v38
	v_rcp_f32_e32 v40, v39
	v_pk_mul_f32 v[18:19], v[22:23], v[18:19]
	v_fma_f32 v42, -v39, v40, 1.0
	v_fmac_f32_e32 v40, v42, v40
	v_div_scale_f32 v42, vcc, v38, v31, v38
	v_mul_f32_e32 v43, v42, v40
	v_fma_f32 v44, -v39, v43, v42
	v_fmac_f32_e32 v43, v44, v40
	v_fma_f32 v39, -v39, v43, v42
	v_div_fmas_f32 v39, v39, v40, v43
	v_div_fixup_f32 v31, v39, v31, v38
	v_div_scale_f32 v38, vcc, v30, v30, v33
	v_rcp_f32_e32 v39, v38
	s_nop 0
	v_fma_f32 v40, -v38, v39, 1.0
	v_fmac_f32_e32 v39, v40, v39
	v_div_scale_f32 v40, vcc, v33, v30, v33
	v_mul_f32_e32 v42, v40, v39
	v_fma_f32 v43, -v38, v42, v40
	v_fmac_f32_e32 v42, v43, v39
	v_fma_f32 v38, -v38, v42, v40
	v_div_fmas_f32 v38, v38, v39, v42
	v_div_fixup_f32 v30, v38, v30, v33
	v_pk_mul_f32 v[18:19], v[30:31], v[18:19]
	v_lshlrev_b32_e32 v30, 16, v41
	v_and_b32_e32 v31, 0xffff0000, v41
	v_mul_f32_e32 v22, 0xbfb8aa3b, v30
	v_mul_f32_e32 v23, 0xbfb8aa3b, v31
	v_exp_f32_e32 v22, v22
	v_exp_f32_e32 v23, v23
	s_nop 0
	v_pk_add_f32 v[22:23], v[22:23], 1.0 op_sel_hi:[1,0]
	s_nop 0
	v_div_scale_f32 v33, vcc, v23, v23, v31
	v_rcp_f32_e32 v38, v33
	s_nop 0
	v_fma_f32 v39, -v33, v38, 1.0
	v_fmac_f32_e32 v38, v39, v38
	v_div_scale_f32 v39, vcc, v31, v23, v31
	v_mul_f32_e32 v40, v39, v38
	v_fma_f32 v41, -v33, v40, v39
	v_fmac_f32_e32 v40, v41, v38
	v_fma_f32 v33, -v33, v40, v39
	v_div_fmas_f32 v33, v33, v38, v40
	v_div_fixup_f32 v23, v33, v23, v31
	v_div_scale_f32 v31, vcc, v22, v22, v30
	v_rcp_f32_e32 v33, v31
	s_nop 0
	v_fma_f32 v38, -v31, v33, 1.0
	v_fmac_f32_e32 v33, v38, v33
	v_div_scale_f32 v38, vcc, v30, v22, v30
	v_mul_f32_e32 v39, v38, v33
	v_fma_f32 v40, -v31, v39, v38
	v_fmac_f32_e32 v39, v40, v33
	v_fma_f32 v31, -v31, v39, v38
	v_div_fmas_f32 v31, v31, v33, v39
	v_pk_mul_f32 v[20:21], v[20:21], v[32:33] op_sel_hi:[1,0]
	v_div_fixup_f32 v22, v31, v22, v30
	v_pk_mul_f32 v[20:21], v[24:25], v[20:21]
	v_lshlrev_b32_e32 v24, 16, v34
	v_and_b32_e32 v25, 0xffff0000, v34
	v_pk_mul_f32 v[20:21], v[22:23], v[20:21]
	v_mul_f32_e32 v22, 0xbfb8aa3b, v24
	v_mul_f32_e32 v23, 0xbfb8aa3b, v25
	v_exp_f32_e32 v22, v22
	v_exp_f32_e32 v23, v23
	s_nop 0
	v_pk_add_f32 v[22:23], v[22:23], 1.0 op_sel_hi:[1,0]
	s_nop 0
	v_div_scale_f32 v30, vcc, v23, v23, v25
	v_rcp_f32_e32 v31, v30
	s_nop 0
	v_fma_f32 v33, -v30, v31, 1.0
	v_fmac_f32_e32 v31, v33, v31
	v_div_scale_f32 v33, vcc, v25, v23, v25
	v_mul_f32_e32 v34, v33, v31
	v_fma_f32 v38, -v30, v34, v33
	v_fmac_f32_e32 v34, v38, v31
	v_fma_f32 v30, -v30, v34, v33
	v_div_fmas_f32 v30, v30, v31, v34
	v_div_fixup_f32 v23, v30, v23, v25
	v_div_scale_f32 v25, vcc, v22, v22, v24
	v_rcp_f32_e32 v30, v25
	s_nop 0
	v_fma_f32 v31, -v25, v30, 1.0
	v_fmac_f32_e32 v30, v31, v30
	v_div_scale_f32 v31, vcc, v24, v22, v24
	v_mul_f32_e32 v33, v31, v30
	v_fma_f32 v34, -v25, v33, v31
	v_fmac_f32_e32 v33, v34, v30
	v_fma_f32 v25, -v25, v33, v31
	v_div_fmas_f32 v25, v25, v30, v33
	v_pk_mul_f32 v[10:11], v[10:11], v[32:33] op_sel_hi:[1,0]
	v_div_fixup_f32 v22, v25, v22, v24
	v_pk_mul_f32 v[10:11], v[14:15], v[10:11]
	s_nop 0
	v_pk_mul_f32 v[10:11], v[22:23], v[10:11]
	v_lshlrev_b32_e32 v22, 16, v35
	v_and_b32_e32 v23, 0xffff0000, v35
	v_mul_f32_e32 v14, 0xbfb8aa3b, v22
	v_mul_f32_e32 v15, 0xbfb8aa3b, v23
	v_exp_f32_e32 v14, v14
	v_exp_f32_e32 v15, v15
	s_nop 0
	v_pk_add_f32 v[14:15], v[14:15], 1.0 op_sel_hi:[1,0]
	s_nop 0
	v_div_scale_f32 v24, vcc, v15, v15, v23
	v_rcp_f32_e32 v25, v24
	s_nop 0
	v_fma_f32 v30, -v24, v25, 1.0
	v_fmac_f32_e32 v25, v30, v25
	v_div_scale_f32 v30, vcc, v23, v15, v23
	v_mul_f32_e32 v31, v30, v25
	v_fma_f32 v33, -v24, v31, v30
	v_fmac_f32_e32 v31, v33, v25
	v_fma_f32 v24, -v24, v31, v30
	v_div_fmas_f32 v24, v24, v25, v31
	v_div_fixup_f32 v15, v24, v15, v23
	v_div_scale_f32 v23, vcc, v14, v14, v22
	v_rcp_f32_e32 v24, v23
	v_pk_mul_f32 v[12:13], v[12:13], v[32:33] op_sel_hi:[1,0]
	v_pk_mul_f32 v[2:3], v[2:3], v[32:33] op_sel_hi:[1,0]
	v_pk_mul_f32 v[12:13], v[16:17], v[12:13]
	v_fma_f32 v25, -v23, v24, 1.0
	v_fmac_f32_e32 v24, v25, v24
	v_div_scale_f32 v25, vcc, v22, v14, v22
	v_mul_f32_e32 v30, v25, v24
	v_fma_f32 v31, -v23, v30, v25
	v_fmac_f32_e32 v30, v31, v24
	v_fma_f32 v23, -v23, v30, v25
	v_div_fmas_f32 v23, v23, v24, v30
	v_div_fixup_f32 v14, v23, v14, v22
; __device__ __forceinline__ void gla_c_item(const Args& a, int l, int item, LAS unsigned char* L, int tid, int wave, int lane, bool smp = false) {
;     ...
;     f32x4 bm0 = {0.f, 0.f, 0.f, 0.f}, bm1 = bm0;
;     if (!smp) { const float* bg = (const float*)(a.out + O_Y) + (size_t)item * 4096 + tid * 8; bm0 = __builtin_nontemporal_load((const f32x4*)bg); bm1 = __builtin_nontemporal_load((const f32x4*)(bg + 4)); }
;     const u32x4 kr = __builtin_nontemporal_load((const u32x4*)((const bf16_t*)(a.ws + WS_GK) + (size_t)(row0 + (tid >> 3)) * 256 + h * 64 + 8 * (tid & 7)));
;     const u32x4 qr = __builtin_nontemporal_load((const u32x4*)((const bf16_t*)(a.ws + WS_GQ) + (size_t)(row0 + (tid >> 3)) * 256 + h * 64 + 8 * (tid & 7)));
;     const bf16_t* Sg = (const bf16_t*)(a.ws + WS_UST) + (size_t)item * 8192 + (tid >> 3) * 128 + 16 * (tid & 7);
;     u32x4 sg0, sg1;
;     if (!smp) { sg0 = __builtin_nontemporal_load((const u32x4*)Sg); sg1 = __builtin_nontemporal_load((const u32x4*)(Sg + 8)); }
;     else {
;         const float* Sf = a.in[4] + (size_t)(l * 32 + item - 1024) * 8192 + (tid >> 3) * 128 + 16 * (tid & 7);
;         const f32x4 f0 = *(const f32x4*)Sf, f1 = *(const f32x4*)(Sf + 4), f2 = *(const f32x4*)(Sf + 8), f3 = *(const f32x4*)(Sf + 12);
;         sg0 = (u32x4){cvtpk(f0[0], f0[1]), cvtpk(f0[2], f0[3]), cvtpk(f1[0], f1[1]), cvtpk(f1[2], f1[3])};
;         sg1 = (u32x4){cvtpk(f2[0], f2[1]), cvtpk(f2[2], f2[3]), cvtpk(f3[0], f3[1]), cvtpk(f3[2], f3[3])};
;     }
;     const bf16_t* vp_ = (const bf16_t*)(a.ws + WS_GV) + (size_t)(row0 + (tid >> 3)) * 512 + h * 128 + 16 * (tid & 7);
;     ...
;         const float* ng = a.in[11] + l * 128 + 16 * sg;
;         float gt[16];
; #pragma unroll
;         for (int i = 0; i < 4; ++i) { gt[2 * i] = bflo(g0[i]); gt[2 * i + 1] = bfhi(g0[i]); gt[8 + 2 * i] = bflo(g1[i]); gt[8 + 2 * i + 1] = bfhi(g1[i]); }
;         float y[16];
; #pragma unroll
;         for (int i = 0; i < 16; ++i) { const float gv = gt[i]; const float sl = gv / (1.0f + __expf(-gv)); y[i] = x[i] * rs * ng[i] * sl; }
;         u32x4 w0, w1;
; #pragma unroll
;         for (int i = 0; i < 4; ++i) { w0[i] = cvtpk(y[2 * i], y[2 * i + 1]); w1[i] = cvtpk(y[8 + 2 * i], y[8 + 2 * i + 1]); }
;         bf16_t* mp = (bf16_t*)(a.ws + WS_MIX) + (size_t)(row0 + t) * D + h * 128 + 16 * sg;
;         *(u32x4*)mp = w0; *(u32x4*)(mp + 8) = w1;
	v_lshlrev_b32_e32 v16, 16, v36
	v_and_b32_e32 v17, 0xffff0000, v36
	v_pk_mul_f32 v[12:13], v[14:15], v[12:13]
	v_mul_f32_e32 v14, 0xbfb8aa3b, v16
	v_mul_f32_e32 v15, 0xbfb8aa3b, v17
	v_exp_f32_e32 v14, v14
	v_exp_f32_e32 v15, v15
	v_pk_mul_f32 v[2:3], v[2:3], v[6:7]
	v_lshlrev_b32_e32 v6, 16, v37
	v_and_b32_e32 v7, 0xffff0000, v37
	v_pk_add_f32 v[14:15], v[14:15], 1.0 op_sel_hi:[1,0]
	v_pk_mul_f32 v[4:5], v[4:5], v[32:33] op_sel_hi:[1,0]
	v_div_scale_f32 v22, vcc, v15, v15, v17
	v_rcp_f32_e32 v23, v22
	v_pk_mul_f32 v[4:5], v[4:5], v[8:9]
	v_fma_f32 v24, -v22, v23, 1.0
	v_fmac_f32_e32 v23, v24, v23
	v_div_scale_f32 v24, vcc, v17, v15, v17
	v_mul_f32_e32 v25, v24, v23
	v_fma_f32 v30, -v22, v25, v24
	v_fmac_f32_e32 v25, v30, v23
	v_fma_f32 v22, -v22, v25, v24
	v_div_fmas_f32 v22, v22, v23, v25
	v_div_fixup_f32 v15, v22, v15, v17
	v_div_scale_f32 v17, vcc, v14, v14, v16
	v_rcp_f32_e32 v22, v17
	s_nop 0
	v_fma_f32 v23, -v17, v22, 1.0
	v_fmac_f32_e32 v22, v23, v22
	v_div_scale_f32 v23, vcc, v16, v14, v16
	v_mul_f32_e32 v24, v23, v22
	v_fma_f32 v25, -v17, v24, v23
	v_fmac_f32_e32 v24, v25, v22
	v_fma_f32 v17, -v17, v24, v23
	v_div_fmas_f32 v17, v17, v22, v24
	v_div_fixup_f32 v14, v17, v14, v16
	v_pk_mul_f32 v[14:15], v[14:15], v[2:3]
	v_mul_f32_e32 v2, 0xbfb8aa3b, v6
	v_mul_f32_e32 v3, 0xbfb8aa3b, v7
	v_exp_f32_e32 v2, v2
	v_exp_f32_e32 v3, v3
	v_cvt_pk_bf16_f32 v8, v14, v15
	v_pk_add_f32 v[2:3], v[2:3], 1.0 op_sel_hi:[1,0]
	s_nop 0
	v_div_scale_f32 v16, vcc, v3, v3, v7
	v_rcp_f32_e32 v17, v16
	s_nop 0
	v_fma_f32 v22, -v16, v17, 1.0
	v_fmac_f32_e32 v17, v22, v17
	v_div_scale_f32 v22, vcc, v7, v3, v7
	v_mul_f32_e32 v23, v22, v17
	v_fma_f32 v24, -v16, v23, v22
	v_fmac_f32_e32 v23, v24, v17
	v_fma_f32 v16, -v16, v23, v22
	v_div_fmas_f32 v16, v16, v17, v23
	v_div_fixup_f32 v3, v16, v3, v7
	v_div_scale_f32 v7, vcc, v2, v2, v6
	v_rcp_f32_e32 v16, v7
	s_nop 0
	v_fma_f32 v17, -v7, v16, 1.0
	v_fmac_f32_e32 v16, v17, v16
	v_div_scale_f32 v17, vcc, v6, v2, v6
	v_mul_f32_e32 v22, v17, v16
	v_fma_f32 v23, -v7, v22, v17
	v_fmac_f32_e32 v22, v23, v16
	v_fma_f32 v7, -v7, v22, v17
	v_div_fmas_f32 v7, v7, v16, v22
	v_div_fixup_f32 v2, v7, v2, v6
	v_cvt_pk_bf16_f32 v6, v10, v11
	v_lshlrev_b64 v[10:11], 11, v[66:67]
	v_lshl_add_u64 v[10:11], s[54:55], 0, v[10:11]
	v_lshl_add_u64 v[10:11], v[10:11], 0, s[82:83]
	v_pk_mul_f32 v[16:17], v[2:3], v[4:5]
	v_cvt_pk_bf16_f32 v2, v28, v29
	v_cvt_pk_bf16_f32 v3, v26, v27
	v_cvt_pk_bf16_f32 v4, v18, v19
	v_cvt_pk_bf16_f32 v5, v20, v21
	v_lshl_add_u64 v[10:11], v[10:11], 0, v[64:65]
	v_cvt_pk_bf16_f32 v7, v12, v13
	v_cvt_pk_bf16_f32 v9, v16, v17
	s_cmpk_gt_i32 s18, 0x3ff
	s_cbranch_scc1 .Lgc_nopf
	global_load_dwordx4 v[124:127], v[112:113], off nt
	global_load_dwordx4 v[128:131], v[112:113], off offset:-16 nt
.Lgc_nopf:
	global_store_dwordx4 v[10:11], v[2:5], off
	global_store_dwordx4 v[10:11], v[6:9], off offset:16
	v_readlane_b32 s54, v246, 41
	s_waitcnt lgkmcnt(0)
	s_barrier
	v_readlane_b32 s55, v246, 42
	s_add_u32 s72, s72, s54
	s_addc_u32 s73, s73, s55
	s_cmpk_gt_i32 s18, 0x3ff
	s_cbranch_scc1 .LBB0_1075
.LBB0_1071:
	s_and_b32 s82, s59, 0xffffffc0
	v_add_u32_e32 v66, s82, v68
	v_ashrrev_i32_e32 v67, 31, v66
	v_readlane_b32 s54, v246, 60
	v_lshlrev_b64 v[10:11], 9, v[66:67]
	v_readlane_b32 s55, v246, 61
	v_lshlrev_b64 v[20:21], 10, v[66:67]
	s_and_b32 s19, s18, 3
	v_lshl_add_u64 v[12:13], s[54:55], 0, v[10:11]
	v_readlane_b32 s54, v246, 16
	v_readlane_b32 s55, v246, 17
	s_lshl_b32 vcc_lo, s19, 8
	s_mov_b32 vcc_hi, s83
	v_lshl_add_u64 v[10:11], s[54:55], 0, v[10:11]
	v_readlane_b32 s54, v247, 26
	v_readlane_b32 s55, v247, 27
	s_lshl_b32 s82, s19, 7
	v_lshl_add_u64 v[18:19], v[60:61], 0, s[72:73]
	v_lshl_add_u64 v[22:23], s[54:55], 0, v[20:21]
	v_readlane_b32 s54, v247, 30
	v_readlane_b32 s55, v247, 31
	v_lshl_add_u64 v[22:23], v[22:23], 0, vcc
	v_mov_b32_e32 v65, v1
	v_lshl_add_u64 v[20:21], s[54:55], 0, v[20:21]
	s_mov_b32 s19, 0xdd00000
	v_lshl_add_u64 v[12:13], v[12:13], 0, s[82:83]
	v_lshl_add_u64 v[10:11], v[10:11], 0, s[82:83]
	v_lshl_add_u64 v[30:31], v[22:23], 0, v[64:65]
	v_lshl_add_u64 v[20:21], v[20:21], 0, vcc
	v_add_co_u32_e32 v22, vcc, s19, v18
	v_lshl_add_u64 v[6:7], v[62:63], 0, s[72:73]
	v_lshl_add_u64 v[12:13], v[12:13], 0, v[0:1]
	v_lshl_add_u64 v[14:15], v[10:11], 0, v[0:1]
	v_lshl_add_u64 v[20:21], v[20:21], 0, v[64:65]
	v_addc_co_u32_e32 v23, vcc, 0, v19, vcc
	s_add_i32 s100, s18, s52
	s_cmpk_gt_i32 s100, 0x3ff
	s_cselect_b32 s100, 0, 0x400000
	s_mov_b32 s101, 0
	v_lshl_add_u64 v[112:113], v[6:7], 0, s[100:101]
	s_cmp_lt_u32 s18, s52
	s_cbranch_scc0 .Lgc_skipbm
	global_load_dwordx4 v[124:127], v[6:7], off nt
	global_load_dwordx4 v[128:131], v[6:7], off offset:-16 nt
.Lgc_skipbm:
	global_load_dwordx4 v[10:13], v[12:13], off nt
	s_nop 0
	global_load_dwordx4 v[14:17], v[14:15], off nt
	s_nop 0
	global_load_dwordx4 v[34:37], v[20:21], off offset:16 nt
	global_load_dwordx4 v[38:41], v[20:21], off nt
	s_nop 0
	global_load_dwordx4 v[18:21], v[22:23], off nt
	s_nop 0
	global_load_dwordx4 v[22:25], v[22:23], off offset:16 nt
	s_nop 0
	global_load_dwordx4 v[26:29], v[30:31], off nt
	s_nop 0
	global_load_dwordx4 v[30:33], v[30:31], off offset:16 nt
	s_cmp_lt_u32 s18, s52
	s_cbranch_scc0 .Lgc_w10
	s_waitcnt vmcnt(8)
	s_branch .Lgc_wdone
.Lgc_w10:
	s_waitcnt vmcnt(10)
; __device__ __forceinline__ void gla_c_item(const Args& a, int l, int item, LAS unsigned char* L, int tid, int wave, int lane, bool smp = false) {
;     ...
;     if (!smp) { *(LAS f32x4*)(Bm + tid * 8) = bm0; *(LAS f32x4*)(Bm + tid * 8 + 4) = bm1; lds_barrier(); }
;     else gla_b(a, l, row0, h, L, tid);
;     {
;         const int s = tid >> 3, dg = tid & 7;
;         u32x4 ko, qo;
; #pragma unroll
;         for (int i = 0; i < 4; ++i) { const int d = 8 * dg + 2 * i; const float b0 = Bm[s * 64 + d], b1 = Bm[s * 64 + d + 1];
;             ko[i] = cvtpk(bflo(kr[i]) * __expf(-b0), bfhi(kr[i]) * __expf(-b1)); qo[i] = cvtpk(bflo(qr[i]) * __expf(b0), bfhi(qr[i]) * __expf(b1)); }
;         *(LAS u32x4*)(KI + s * 72 + 8 * dg) = ko; *(LAS u32x4*)(QD + s * 72 + 8 * dg) = qo;
; #pragma unroll
;         for (int j = 0; j < 4; ++j) { const unsigned w0 = j < 2 ? sg0[2 * j] : sg1[2 * j - 4], w1 = j < 2 ? sg0[2 * j + 1] : sg1[2 * j - 3];
;             ST[(16 * dg + 4 * j) * 72 + (s ^ (8 * dg))] = (bf16_t)(w0 & 0xffffu); ST[(16 * dg + 4 * j + 1) * 72 + (s ^ (8 * dg))] = (bf16_t)(w0 >> 16);
;             ST[(16 * dg + 4 * j + 2) * 72 + (s ^ (8 * dg))] = (bf16_t)(w1 & 0xffffu); ST[(16 * dg + 4 * j + 3) * 72 + (s ^ (8 * dg))] = (bf16_t)(w1 >> 16); }
;     }
;     gla_vt(pv0, pv1, L, tid);
;     lds_barrier();
;     {
;         const int r32 = lane & 31, hi = lane >> 5, ti = wave >> 2, vi = wave & 3;
;         bf16x8 qf[4];
; #pragma unroll
;         for (int kd = 0; kd < 4; ++kd) qf[kd] = *(const LAS bf16x8*)(QD + (32 * ti + r32) * 72 + 16 * kd + 8 * hi);
;         f32x16 o;
; #pragma unroll
;         for (int i = 0; i < 16; ++i) o[i] = 0.f;
; #pragma unroll
;         for (int kd = 0; kd < 4; ++kd) { const int srow = 32 * vi + r32; o = MFMA32(qf[kd], *(const LAS bf16x8*)(ST + srow * 72 + ((16 * kd + 8 * hi) ^ (8 * ((srow >> 4) & 7)))), o); }
;         const int tcol = 32 * ti + r32;
; #pragma unroll
;         for (int sb = 0; sb < 2; ++sb) {
;             if (sb <= ti) {
;                 f32x16 sc;
; #pragma unroll
;                 for (int i = 0; i < 16; ++i) sc[i] = 0.f;
; #pragma unroll
;                 for (int kd = 0; kd < 4; ++kd) sc = MFMA32(*(const LAS bf16x8*)(KI + (32 * sb + r32) * 72 + 16 * kd + 8 * hi), qf[kd], sc);
; #pragma unroll
;                 for (int r = 0; r < 16; ++r) { const int srow = 32 * sb + crow(r, hi); if (srow > tcol) sc[r] = 0.f; }
; #pragma unroll
.Lgc_wdone:
	ds_write_b128 v86, v[128:131]
	ds_write_b128 v86, v[124:127] offset:16
	s_waitcnt lgkmcnt(0)
	s_barrier
	ds_read_b128 v[2:5], v69
	ds_read_b128 v[6:9], v69 offset:16
	s_waitcnt vmcnt(7)
	v_lshlrev_b32_e32 v44, 16, v10
	v_and_b32_e32 v45, 0xffff0000, v10
	s_andn2_b64 vcc, exec, s[4:5]
	s_waitcnt lgkmcnt(1)
	v_mul_f32_e32 v42, 0xbfb8aa3b, v2
	v_mul_f32_e32 v43, 0xbfb8aa3b, v3
	v_exp_f32_e32 v42, v42
	v_exp_f32_e32 v43, v43
	v_mul_f32_e32 v2, 0x3fb8aa3b, v2
	v_mul_f32_e32 v3, 0x3fb8aa3b, v3
	v_exp_f32_e32 v2, v2
	v_exp_f32_e32 v3, v3
	v_pk_mul_f32 v[42:43], v[42:43], v[44:45]
	v_lshlrev_b32_e32 v44, 16, v11
	v_cvt_pk_bf16_f32 v10, v42, v43
	s_waitcnt vmcnt(6)
	v_lshlrev_b32_e32 v42, 16, v14
	v_and_b32_e32 v43, 0xffff0000, v14
	v_pk_mul_f32 v[2:3], v[2:3], v[42:43]
	v_lshlrev_b32_e32 v14, 16, v15
	v_cvt_pk_bf16_f32 v2, v2, v3
	v_mul_f32_e32 v3, 0xbfb8aa3b, v4
	v_exp_f32_e32 v42, v3
	v_mul_f32_e32 v3, 0xbfb8aa3b, v5
	v_exp_f32_e32 v43, v3
	v_mul_f32_e32 v3, 0x3fb8aa3b, v4
	v_exp_f32_e32 v4, v3
	v_mul_f32_e32 v3, 0x3fb8aa3b, v5
	v_exp_f32_e32 v5, v3
	v_and_b32_e32 v15, 0xffff0000, v15
	v_and_b32_e32 v45, 0xffff0000, v11
	v_pk_mul_f32 v[42:43], v[42:43], v[44:45]
	v_pk_mul_f32 v[4:5], v[4:5], v[14:15]
	v_lshlrev_b32_e32 v14, 16, v12
	v_cvt_pk_bf16_f32 v3, v4, v5
	s_waitcnt lgkmcnt(0)
	v_mul_f32_e32 v4, 0xbfb8aa3b, v6
	v_mul_f32_e32 v5, 0xbfb8aa3b, v7
	v_exp_f32_e32 v4, v4
	v_exp_f32_e32 v5, v5
	v_and_b32_e32 v15, 0xffff0000, v12
	v_cvt_pk_bf16_f32 v11, v42, v43
	v_pk_mul_f32 v[4:5], v[4:5], v[14:15]
	s_nop 0
	v_cvt_pk_bf16_f32 v12, v4, v5
	v_mul_f32_e32 v4, 0x3fb8aa3b, v6
	v_mul_f32_e32 v5, 0x3fb8aa3b, v7
	v_exp_f32_e32 v4, v4
	v_exp_f32_e32 v5, v5
	v_lshlrev_b32_e32 v6, 16, v16
	v_and_b32_e32 v7, 0xffff0000, v16
	v_lshlrev_b32_e32 v14, 16, v13
	v_pk_mul_f32 v[4:5], v[4:5], v[6:7]
	v_and_b32_e32 v15, 0xffff0000, v13
	v_cvt_pk_bf16_f32 v4, v4, v5
	v_mul_f32_e32 v5, 0xbfb8aa3b, v8
	v_exp_f32_e32 v6, v5
	v_mul_f32_e32 v5, 0xbfb8aa3b, v9
	v_exp_f32_e32 v7, v5
	v_mul_f32_e32 v5, 0x3fb8aa3b, v8
	v_lshlrev_b32_e32 v8, 16, v17
	v_pk_mul_f32 v[6:7], v[6:7], v[14:15]
	s_nop 0
	v_cvt_pk_bf16_f32 v13, v6, v7
	v_exp_f32_e32 v6, v5
	v_mul_f32_e32 v5, 0x3fb8aa3b, v9
	v_exp_f32_e32 v7, v5
	v_and_b32_e32 v9, 0xffff0000, v17
	v_pk_mul_f32 v[6:7], v[6:7], v[8:9]
	s_nop 0
	v_cvt_pk_bf16_f32 v5, v6, v7
	ds_write_b128 v70, v[10:13] offset:32768
	ds_write_b128 v70, v[2:5] offset:41984
	s_waitcnt vmcnt(3)
	ds_write_b16 v71, v18
	ds_write_b16_d16_hi v71, v18 offset:144
	ds_write_b16 v71, v19 offset:288
	ds_write_b16_d16_hi v71, v19 offset:432
	ds_write_b16 v71, v20 offset:576
	ds_write_b16_d16_hi v71, v20 offset:720
	ds_write_b16 v71, v21 offset:864
	ds_write_b16_d16_hi v71, v21 offset:1008
	s_waitcnt vmcnt(2)
	ds_write_b16 v71, v22 offset:1152
	ds_write_b16_d16_hi v71, v22 offset:1296
	ds_write_b16 v71, v23 offset:1440
	ds_write_b16_d16_hi v71, v23 offset:1584
	ds_write_b16 v71, v24 offset:1728
	ds_write_b16_d16_hi v71, v24 offset:1872
	ds_write_b16 v71, v25 offset:2016
	ds_write_b16_d16_hi v71, v25 offset:2160
	s_waitcnt vmcnt(1)
	ds_write_b16 v72, v26 offset:51200
	ds_write_b16_d16_hi v72, v26 offset:51344
	s_waitcnt vmcnt(0)
	ds_write_b16 v72, v30 offset:52352
	ds_write_b16_d16_hi v72, v30 offset:52496
	ds_write_b16 v72, v27 offset:51488
	ds_write_b16_d16_hi v72, v27 offset:51632
	ds_write_b16 v72, v31 offset:52640
	ds_write_b16_d16_hi v72, v31 offset:52784
	ds_write_b16 v72, v28 offset:51776
	ds_write_b16_d16_hi v72, v28 offset:51920
	ds_write_b16 v72, v32 offset:52928
	ds_write_b16_d16_hi v72, v32 offset:53072
	ds_write_b16 v72, v29 offset:52064
	ds_write_b16_d16_hi v72, v29 offset:52208
	ds_write_b16 v72, v33 offset:53216
	ds_write_b16_d16_hi v72, v33 offset:53360
	s_waitcnt lgkmcnt(0)
	s_barrier
	ds_read_b128 v[54:57], v87 offset:41984
	ds_read_b128 v[50:53], v87 offset:42016
	ds_read_b128 v[46:49], v87 offset:42048
	ds_read_b128 v[42:45], v87 offset:42080
	ds_read_b128 v[2:5], v73
	s_waitcnt lgkmcnt(0)
	v_mfma_f32_32x32x16_bf16 v[2:17], v[54:57], v[2:5], 0
	ds_read_b128 v[18:21], v74
	s_waitcnt lgkmcnt(0)
	v_mfma_f32_32x32x16_bf16 v[2:17], v[50:53], v[18:21], v[2:17]
	ds_read_b128 v[18:21], v75
	s_waitcnt lgkmcnt(0)
	v_mfma_f32_32x32x16_bf16 v[2:17], v[46:49], v[18:21], v[2:17]
	ds_read_b128 v[18:21], v76
	s_waitcnt lgkmcnt(0)
	v_mfma_f32_32x32x16_bf16 v[2:17], v[42:45], v[18:21], v[2:17]
	s_cbranch_vccnz .LBB0_1073
	ds_read_b128 v[18:21], v88 offset:32768
	ds_read_b128 v[92:95], v88 offset:32800
	v_readlane_b32 s54, v248, 9
	v_readlane_b32 s55, v248, 10
	s_waitcnt lgkmcnt(1)
	v_mfma_f32_32x32x16_bf16 v[18:33], v[18:21], v[54:57], 0
	s_waitcnt lgkmcnt(0)
	v_mfma_f32_32x32x16_bf16 v[18:33], v[92:95], v[50:53], v[18:33]
	ds_read_b128 v[92:95], v88 offset:32832
	s_waitcnt lgkmcnt(0)
	v_mfma_f32_32x32x16_bf16 v[18:33], v[92:95], v[46:49], v[18:33]
	ds_read_b128 v[92:95], v88 offset:32864
	s_waitcnt lgkmcnt(0)
	v_mfma_f32_32x32x16_bf16 v[18:33], v[92:95], v[42:45], v[18:33]
	s_nop 11
	v_cndmask_b32_e64 v20, v20, 0, s[54:55]
	v_readlane_b32 s54, v248, 21
	v_readlane_b32 s55, v248, 22
	v_cndmask_b32_e64 v65, v18, 0, s[56:57]
	v_cndmask_b32_e64 v18, v65, v18, s[8:9]
	v_cndmask_b32_e64 v21, v21, 0, s[54:55]
	v_readlane_b32 s54, v248, 23
	v_readlane_b32 s55, v248, 24
	v_cndmask_b32_e64 v19, 0, v19, s[8:9]
	v_cndmask_b32_e64 v25, v25, 0, s[20:21]
	v_cndmask_b32_e64 v22, v22, 0, s[54:55]
	v_readlane_b32 s54, v248, 25
	v_readlane_b32 s55, v248, 26
	v_cvt_pk_bf16_f32 v18, v18, v19
	v_cvt_pk_bf16_f32 v19, v20, v21
	v_cndmask_b32_e64 v23, v23, 0, s[54:55]
	v_readlane_b32 s54, v248, 27
	v_readlane_b32 s55, v248, 28
	v_cvt_pk_bf16_f32 v20, v22, v23
	v_cndmask_b32_e64 v26, v26, 0, s[22:23]
	v_cndmask_b32_e64 v24, v24, 0, s[54:55]
	v_cvt_pk_bf16_f32 v21, v24, v25
	ds_read_b64 v[22:23], v77 offset:51200
	ds_read_b64 v[24:25], v78 offset:51200
	s_waitcnt lgkmcnt(0)
	v_mfma_f32_32x32x16_bf16 v[2:17], v[18:21], v[22:25], v[2:17]
	v_cndmask_b32_e64 v27, v27, 0, s[24:25]
	v_cndmask_b32_e64 v28, v28, 0, s[26:27]
	v_cndmask_b32_e64 v29, v29, 0, s[28:29]
	v_cndmask_b32_e64 v30, v30, 0, s[30:31]
	v_cndmask_b32_e64 v31, v31, 0, s[34:35]
	v_cndmask_b32_e64 v32, v32, 0, s[36:37]
	v_cndmask_b32_e64 v33, v33, 0, s[38:39]
	v_cvt_pk_bf16_f32 v18, v26, v27
	v_cvt_pk_bf16_f32 v19, v28, v29
	v_cvt_pk_bf16_f32 v20, v30, v31
	v_cvt_pk_bf16_f32 v21, v32, v33
	ds_read_b64 v[22:23], v79 offset:51200
	ds_read_b64 v[24:25], v80 offset:51200
	s_waitcnt lgkmcnt(0)
	v_mfma_f32_32x32x16_bf16 v[2:17], v[18:21], v[22:25], v[2:17]

; __global__ void __launch_bounds__(512, 2) fwd_kernel(Args a) {
;     extern __shared__ __attribute__((aligned(16))) unsigned char lds_raw[];
	.amdhsa_kernel _Z10fwd_kernel4Args
		.amdhsa_group_segment_fixed_size 0
		.amdhsa_private_segment_fixed_size 0
		.amdhsa_kernarg_size 400
		.amdhsa_user_sgpr_count 2
		.amdhsa_user_sgpr_dispatch_ptr 0
		.amdhsa_user_sgpr_queue_ptr 0
		.amdhsa_user_sgpr_kernarg_segment_ptr 1
		.amdhsa_user_sgpr_dispatch_id 0
		.amdhsa_user_sgpr_kernarg_preload_length 0
		.amdhsa_user_sgpr_kernarg_preload_offset 0
		.amdhsa_user_sgpr_private_segment_size 0
		.amdhsa_uses_dynamic_stack 0
		.amdhsa_enable_private_segment 0
		.amdhsa_system_sgpr_workgroup_id_x 1
		.amdhsa_system_sgpr_workgroup_id_y 0
		.amdhsa_system_sgpr_workgroup_id_z 0
		.amdhsa_system_sgpr_workgroup_info 0
		.amdhsa_system_vgpr_workitem_id 2
		.amdhsa_next_free_vgpr 250
		.amdhsa_next_free_sgpr 102
		.amdhsa_accum_offset 252
		.amdhsa_reserve_vcc 1
		.amdhsa_float_round_mode_32 0
		.amdhsa_float_round_mode_16_64 0
		.amdhsa_float_denorm_mode_32 3
		.amdhsa_float_denorm_mode_16_64 3
		.amdhsa_dx10_clamp 1
		.amdhsa_ieee_mode 1
		.amdhsa_fp16_overflow 0
		.amdhsa_tg_split 0
		.amdhsa_exception_fp_ieee_invalid_op 0
		.amdhsa_exception_fp_denorm_src 0
		.amdhsa_exception_fp_ieee_div_zero 0
		.amdhsa_exception_fp_ieee_overflow 0
		.amdhsa_exception_fp_ieee_underflow 0
		.amdhsa_exception_fp_ieee_inexact 0
		.amdhsa_exception_int_div_zero 0
	.end_amdhsa_kernel

; __global__ void __launch_bounds__(512, 2) fwd_kernel(Args a) {
;     extern __shared__ __attribute__((aligned(16))) unsigned char lds_raw[];
amdhsa.kernels:
  - .agpr_count:     0
    .args:
      - .offset:         0
        .size:           144
        .value_kind:     by_value
      - .offset:         144
        .size:           4
        .value_kind:     hidden_block_count_x
      - .offset:         148
        .size:           4
        .value_kind:     hidden_block_count_y
      - .offset:         152
        .size:           4
        .value_kind:     hidden_block_count_z
      - .offset:         156
        .size:           2
        .value_kind:     hidden_group_size_x
      - .offset:         158
        .size:           2
        .value_kind:     hidden_group_size_y
      - .offset:         160
        .size:           2
        .value_kind:     hidden_group_size_z
      - .offset:         162
        .size:           2
        .value_kind:     hidden_remainder_x
      - .offset:         164
        .size:           2
        .value_kind:     hidden_remainder_y
      - .offset:         166
        .size:           2
        .value_kind:     hidden_remainder_z
      - .offset:         184
        .size:           8
        .value_kind:     hidden_global_offset_x
      - .offset:         192
        .size:           8
        .value_kind:     hidden_global_offset_y
      - .offset:         200
        .size:           8
        .value_kind:     hidden_global_offset_z
      - .offset:         208
        .size:           2
        .value_kind:     hidden_grid_dims
      - .offset:         232
        .size:           8
        .value_kind:     hidden_multigrid_sync_arg
      - .offset:         264
        .size:           4
        .value_kind:     hidden_dynamic_lds_size
    .group_segment_fixed_size: 0
    .kernarg_segment_align: 8
    .kernarg_segment_size: 400
    .language:       OpenCL C
    .language_version:
      - 2
      - 0
    .max_flat_workgroup_size: 512
    .name:           _Z10fwd_kernel4Args
    .private_segment_fixed_size: 0
    .sgpr_count:     108
    .sgpr_spill_count: 223
    .symbol:         _Z10fwd_kernel4Args.kd
    .uniform_work_group_size: 1
    .uses_dynamic_stack: false
    .vgpr_count:     250
    .vgpr_spill_count: 0
    .wavefront_size: 64
